# ret_out epilogue: xor-1/2/4/8 butterfly steps use DPP moves (quad_perm, row_half_mirror, row_mirror) instead of ds_bpermute round trips
# baseline (speedup 1.0000x reference)
; __device__ __forceinline__ int crow(int r, int hi) { return (r & 3) + 8 * (r >> 2) + 4 * hi; }
; __device__ __forceinline__ void ret_out_unit(bf16_t* Qb  , const bf16_t* __restrict__ Kh, const bf16_t* __restrict__ Vh, const bf16_t* __restrict__ Sf, const bf16_t* __restrict__ Sb,
;                                              const bf16_t* Gb, float lf2, float lb2, char* lds) {
;     ...
;   bf16_t* Ow = Qb + (long)(wid * QBLK) * 1024; const bf16_t* Gw = Gb + (long)(wid * QBLK) * 512;
; #pragma unroll
;   for (int r = 0; r < 16; ++r) {
;     float ss = (o[0][r] * o[0][r] + o[1][r] * o[1][r]) + (o[2][r] * o[2][r] + o[3][r] * o[3][r]);
; #pragma unroll
;     for (int off = 1; off < 32; off <<= 1) ss += __shfl_xor(ss, off);
;     const float rs = rsqrtf(ss * (1.f / 128.f) + EPS_N); const int orow = crow(r, hi);
.LBB0_1952:
	s_lshl_b64 s[56:57], s[56:57], 1
	s_add_u32 s6, s15, s56
	s_addc_u32 s57, s35, s57
	s_lshl_b32 s56, s70, 1
	s_add_u32 s56, s6, s56
	v_ashrrev_i32_e32 v149, 31, v148
	s_addc_u32 s57, s57, 0
	v_lshlrev_b64 v[66:67], 11, v[148:149]
	v_lshlrev_b64 v[68:69], 10, v[148:149]
	v_lshl_add_u64 v[66:67], s[4:5], 0, v[66:67]
	v_lshl_add_u64 v[68:69], s[56:57], 0, v[68:69]
	v_lshlrev_b32_e32 v146, 1, v229
	v_lshl_add_u64 v[68:69], v[68:69], 0, v[146:147]
	v_lshl_add_u64 v[66:67], v[66:67], 0, v[146:147]
	v_lshlrev_b32_e32 v146, 10, v228
	v_lshl_add_u64 v[70:71], v[68:69], 0, v[146:147]
	v_mov_b32_e32 v181, 0
	v_lshlrev_b32_e32 v180, 10, v228
	v_lshl_add_u64 v[182:183], v[68:69], 0, v[180:181]
	global_load_ushort v110, v[182:183], off
	global_load_ushort v111, v[182:183], off offset:64
	global_load_ushort v112, v[182:183], off offset:128
	global_load_ushort v113, v[182:183], off offset:192
	v_or_b32_e32 v180, 1, v228
	v_lshlrev_b32_e32 v180, 10, v180
	v_lshl_add_u64 v[182:183], v[68:69], 0, v[180:181]
	global_load_ushort v114, v[182:183], off
	global_load_ushort v115, v[182:183], off offset:64
	global_load_ushort v116, v[182:183], off offset:128
	global_load_ushort v117, v[182:183], off offset:192
	v_or_b32_e32 v180, 2, v228
	v_lshlrev_b32_e32 v180, 10, v180
	v_lshl_add_u64 v[182:183], v[68:69], 0, v[180:181]
	global_load_ushort v118, v[182:183], off
	global_load_ushort v119, v[182:183], off offset:64
	global_load_ushort v120, v[182:183], off offset:128
	global_load_ushort v121, v[182:183], off offset:192
	v_or_b32_e32 v180, 3, v228
	v_lshlrev_b32_e32 v180, 10, v180
	v_lshl_add_u64 v[182:183], v[68:69], 0, v[180:181]
	global_load_ushort v122, v[182:183], off
	global_load_ushort v123, v[182:183], off offset:64
	global_load_ushort v124, v[182:183], off offset:128
	global_load_ushort v125, v[182:183], off offset:192
	v_or_b32_e32 v180, 8, v228
	v_lshlrev_b32_e32 v180, 10, v180
	v_lshl_add_u64 v[182:183], v[68:69], 0, v[180:181]
	global_load_ushort v126, v[182:183], off
	global_load_ushort v127, v[182:183], off offset:64
	global_load_ushort v128, v[182:183], off offset:128
	global_load_ushort v129, v[182:183], off offset:192
	v_or_b32_e32 v180, 9, v228
	v_lshlrev_b32_e32 v180, 10, v180
	v_lshl_add_u64 v[182:183], v[68:69], 0, v[180:181]
	global_load_ushort v130, v[182:183], off
	global_load_ushort v131, v[182:183], off offset:64
	global_load_ushort v132, v[182:183], off offset:128
	global_load_ushort v133, v[182:183], off offset:192
	v_or_b32_e32 v180, 10, v228
	v_lshlrev_b32_e32 v180, 10, v180
	v_lshl_add_u64 v[182:183], v[68:69], 0, v[180:181]
	global_load_ushort v134, v[182:183], off
	global_load_ushort v135, v[182:183], off offset:64
	global_load_ushort v136, v[182:183], off offset:128
	global_load_ushort v137, v[182:183], off offset:192
	v_or_b32_e32 v180, 11, v228
	v_lshlrev_b32_e32 v180, 10, v180
	v_lshl_add_u64 v[182:183], v[68:69], 0, v[180:181]
	global_load_ushort v138, v[182:183], off
	global_load_ushort v139, v[182:183], off offset:64
	global_load_ushort v140, v[182:183], off offset:128
	global_load_ushort v141, v[182:183], off offset:192
	v_or_b32_e32 v180, 16, v228
	v_lshlrev_b32_e32 v180, 10, v180
	v_lshl_add_u64 v[182:183], v[68:69], 0, v[180:181]
	global_load_ushort v142, v[182:183], off
	global_load_ushort v143, v[182:183], off offset:64
	global_load_ushort v144, v[182:183], off offset:128
	global_load_ushort v145, v[182:183], off offset:192
	v_or_b32_e32 v180, 17, v228
	v_lshlrev_b32_e32 v180, 10, v180
	v_lshl_add_u64 v[182:183], v[68:69], 0, v[180:181]
	global_load_ushort v150, v[182:183], off
	global_load_ushort v151, v[182:183], off offset:64
	global_load_ushort v152, v[182:183], off offset:128
	global_load_ushort v153, v[182:183], off offset:192
	v_or_b32_e32 v180, 18, v228
	v_lshlrev_b32_e32 v180, 10, v180
	v_lshl_add_u64 v[182:183], v[68:69], 0, v[180:181]
	global_load_ushort v154, v[182:183], off
	global_load_ushort v155, v[182:183], off offset:64
	global_load_ushort v156, v[182:183], off offset:128
	global_load_ushort v157, v[182:183], off offset:192
	v_or_b32_e32 v180, 19, v228
	v_lshlrev_b32_e32 v180, 10, v180
	v_lshl_add_u64 v[182:183], v[68:69], 0, v[180:181]
	global_load_ushort v158, v[182:183], off
	global_load_ushort v159, v[182:183], off offset:64
	global_load_ushort v160, v[182:183], off offset:128
	global_load_ushort v161, v[182:183], off offset:192
	v_or_b32_e32 v180, 24, v228
	v_lshlrev_b32_e32 v180, 10, v180
	v_lshl_add_u64 v[182:183], v[68:69], 0, v[180:181]
	global_load_ushort v162, v[182:183], off
	global_load_ushort v163, v[182:183], off offset:64
	global_load_ushort v164, v[182:183], off offset:128
	global_load_ushort v165, v[182:183], off offset:192
	v_or_b32_e32 v180, 25, v228
	v_lshlrev_b32_e32 v180, 10, v180
	v_lshl_add_u64 v[182:183], v[68:69], 0, v[180:181]
	global_load_ushort v166, v[182:183], off
	global_load_ushort v167, v[182:183], off offset:64
	global_load_ushort v168, v[182:183], off offset:128
	global_load_ushort v169, v[182:183], off offset:192
	v_or_b32_e32 v180, 26, v228
	v_lshlrev_b32_e32 v180, 10, v180
	v_lshl_add_u64 v[182:183], v[68:69], 0, v[180:181]
	global_load_ushort v172, v[182:183], off
	global_load_ushort v173, v[182:183], off offset:64
	global_load_ushort v174, v[182:183], off offset:128
	global_load_ushort v175, v[182:183], off offset:192
	v_or_b32_e32 v180, 27, v228
	v_lshlrev_b32_e32 v180, 10, v180
	v_lshl_add_u64 v[182:183], v[68:69], 0, v[180:181]
	global_load_ushort v176, v[182:183], off
	global_load_ushort v177, v[182:183], off offset:64
	global_load_ushort v178, v[182:183], off offset:128
	global_load_ushort v179, v[182:183], off offset:192
	v_and_b32_e32 v78, 64, v227
	v_mov_b32_e32 v72, v34
	v_mov_b32_e32 v73, v2
	v_mov_b32_e32 v76, v35
	v_mov_b32_e32 v77, v3
	v_mov_b32_e32 v70, v50
	v_mov_b32_e32 v71, v18
	v_xor_b32_e32 v79, 1, v227
	v_mov_b32_e32 v74, v51
	v_mov_b32_e32 v75, v19
	v_add_u32_e32 v80, 64, v78
	v_pk_mul_f32 v[72:73], v[72:73], v[72:73]
	v_pk_mul_f32 v[76:77], v[76:77], v[76:77]
	v_pk_fma_f32 v[70:71], v[70:71], v[70:71], v[72:73]
	v_cmp_lt_i32_e32 vcc, v79, v80
	v_pk_fma_f32 v[74:75], v[74:75], v[74:75], v[76:77]
	v_mov_b32_e32 v77, v70
	v_cndmask_b32_e32 v72, v227, v79, vcc
	v_mov_b32_e32 v76, v74
	v_mov_b32_e32 v70, v75
	v_lshlrev_b32_e32 v72, 2, v72
	v_pk_add_f32 v[70:71], v[76:77], v[70:71]
	s_nop 1
	v_mov_b32_dpp v75, v71 quad_perm:[1,0,3,2] row_mask:0xf bank_mask:0xf
	s_nop 1
	v_mov_b32_dpp v74, v70 quad_perm:[1,0,3,2] row_mask:0xf bank_mask:0xf
	v_xor_b32_e32 v73, 2, v227
	v_cmp_lt_i32_e32 vcc, v73, v80
	v_lshlrev_b32_e32 v146, 11, v228
	v_lshl_add_u64 v[82:83], v[66:67], 0, v[146:147]
	v_cndmask_b32_e32 v73, v227, v73, vcc
	v_lshlrev_b32_e32 v73, 2, v73
	s_waitcnt lgkmcnt(0)
; __device__ __forceinline__ float bf1(bf16_t h) { return __uint_as_float(((unsigned)h) << 16); }
; __device__ __forceinline__ bf16_t f2bf(float f) { return (bf16_t)(pk2(f, 0.f) & 0xffffu); }
; __device__ __forceinline__ float silu_t(float x) { return x * fast_sigmoid(x); }
; __device__ __forceinline__ int crow(int r, int hi) { return (r & 3) + 8 * (r >> 2) + 4 * hi; }
; __device__ __forceinline__ void ret_out_unit(bf16_t* Qb  , const bf16_t* __restrict__ Kh, const bf16_t* __restrict__ Vh, const bf16_t* __restrict__ Sf, const bf16_t* __restrict__ Sb,
;                                              const bf16_t* Gb, float lf2, float lb2, char* lds) {
;     ...
;   for (int r = 0; r < 16; ++r) {
;     float ss = (o[0][r] * o[0][r] + o[1][r] * o[1][r]) + (o[2][r] * o[2][r] + o[3][r] * o[3][r]);
; #pragma unroll
;     for (int off = 1; off < 32; off <<= 1) ss += __shfl_xor(ss, off);
;     const float rs = rsqrtf(ss * (1.f / 128.f) + EPS_N); const int orow = crow(r, hi);
; #pragma unroll
;     for (int d0 = 0; d0 < 4; ++d0) { const float g = bf1(Gw[(long)orow * 512 + d0 * 32 + r32]); Ow[(long)orow * 1024 + d0 * 32 + r32] = f2bf(o[d0][r] * rs * silu_t(g)); }
	v_pk_add_f32 v[70:71], v[70:71], v[74:75]
	s_nop 1
	v_mov_b32_dpp v77, v71 quad_perm:[2,3,0,1] row_mask:0xf bank_mask:0xf
	s_nop 1
	v_mov_b32_dpp v76, v70 quad_perm:[2,3,0,1] row_mask:0xf bank_mask:0xf
	v_xor_b32_e32 v74, 4, v227
	v_cmp_lt_i32_e32 vcc, v74, v80
	v_xor_b32_e32 v75, 8, v227
	s_waitcnt lgkmcnt(0)
	v_pk_add_f32 v[70:71], v[70:71], v[76:77]
	v_cndmask_b32_e32 v74, v227, v74, vcc
	v_lshlrev_b32_e32 v74, 2, v74
	s_nop 1
	v_mov_b32_dpp v77, v71 row_half_mirror row_mask:0xf bank_mask:0xf
	s_nop 1
	v_mov_b32_dpp v76, v70 row_half_mirror row_mask:0xf bank_mask:0xf
	v_cmp_lt_i32_e32 vcc, v75, v80
	s_waitcnt lgkmcnt(0)
	v_pk_add_f32 v[70:71], v[70:71], v[76:77]
	v_cndmask_b32_e32 v75, v227, v75, vcc
	v_lshlrev_b32_e32 v75, 2, v75
	s_nop 1
	v_mov_b32_dpp v79, v71 row_mirror row_mask:0xf bank_mask:0xf
	s_nop 1
	v_mov_b32_dpp v78, v70 row_mirror row_mask:0xf bank_mask:0xf
	v_xor_b32_e32 v76, 16, v227
	v_cmp_lt_i32_e32 vcc, v76, v80
	s_waitcnt lgkmcnt(0)
	v_pk_add_f32 v[78:79], v[70:71], v[78:79]
	v_cndmask_b32_e32 v76, v227, v76, vcc
	v_lshlrev_b32_e32 v76, 2, v76
	ds_bpermute_b32 v81, v76, v79
	ds_bpermute_b32 v80, v76, v78
	v_mov_b64_e32 v[70:71], s[52:53]
	s_waitcnt lgkmcnt(0)
	v_pk_add_f32 v[78:79], v[78:79], v[80:81]
	s_nop 0
	v_pk_fma_f32 v[78:79], v[78:79], s[48:49], v[70:71] op_sel_hi:[1,0,0]
	s_waitcnt vmcnt(60)
	v_lshlrev_b32_e32 v80, 16, v110
	v_lshlrev_b32_e32 v81, 16, v111
	v_lshlrev_b32_e32 v84, 16, v112
	v_lshlrev_b32_e32 v85, 16, v113
	v_mul_f32_e32 v88, 0xbfb8aa3b, v84
	v_mul_f32_e32 v89, 0xbfb8aa3b, v85
	v_exp_f32_e32 v88, v88
	v_exp_f32_e32 v89, v89
	v_mul_f32_e32 v86, 0xbfb8aa3b, v80
	v_mul_f32_e32 v87, 0xbfb8aa3b, v81
	v_exp_f32_e32 v86, v86
	v_exp_f32_e32 v87, v87
	v_mul_f32_e32 v77, 0x4b800000, v79
	v_cmp_gt_f32_e32 vcc, s69, v79
	v_add_f32_e32 v88, 1.0, v88
	v_add_f32_e32 v89, 1.0, v89
	v_cndmask_b32_e32 v77, v79, v77, vcc
	v_rcp_f32_e32 v88, v88
	v_rcp_f32_e32 v89, v89
	v_rsq_f32_e32 v77, v77
	v_add_f32_e32 v86, 1.0, v86
	v_add_f32_e32 v87, 1.0, v87
	v_rcp_f32_e32 v86, v86
	v_rcp_f32_e32 v87, v87
	v_mul_f32_e32 v79, v88, v84
	v_mul_f32_e32 v84, v89, v85
	v_mul_f32_e32 v85, 0x45800000, v77
	v_cndmask_b32_e32 v77, v77, v85, vcc
	v_mul_f32_e32 v80, v86, v80
	v_mul_f32_e32 v81, v87, v81
	v_mul_f32_e32 v50, v50, v77
	v_mul_f32_e32 v34, v34, v77
	v_mul_f32_e32 v18, v18, v77
	v_mul_f32_e32 v2, v2, v77
	v_mul_f32_e32 v50, v80, v50
	v_mul_f32_e32 v34, v34, v81
	v_mul_f32_e32 v18, v18, v79
	v_mul_f32_e32 v2, v2, v84
	v_cmp_gt_f32_e64 s[4:5], s69, v78
	v_cvt_pk_bf16_f32 v50, v50, s0
	v_cvt_pk_bf16_f32 v34, v34, s0
	v_cvt_pk_bf16_f32 v18, v18, s0
	v_cvt_pk_bf16_f32 v2, v2, s0
	global_store_short v[82:83], v50, off
	global_store_short v[82:83], v34, off offset:64
	global_store_short v[82:83], v18, off offset:128
	global_store_short v[82:83], v2, off offset:192
	v_or_b32_e32 v2, 1, v228
	v_lshlrev_b32_e32 v146, 10, v2
	v_lshl_add_u64 v[80:81], v[68:69], 0, v[146:147]
	v_mul_f32_e32 v79, 0x4b800000, v78
	v_cndmask_b32_e64 v78, v78, v79, s[4:5]
	v_rsq_f32_e32 v80, v78
	v_lshlrev_b32_e32 v146, 11, v2
	v_lshl_add_u64 v[78:79], v[66:67], 0, v[146:147]
	v_mul_f32_e32 v2, 0x45800000, v80
	v_cndmask_b32_e64 v2, v80, v2, s[4:5]
	v_mul_f32_e32 v51, v51, v2
	v_mul_f32_e32 v35, v35, v2
	v_mul_f32_e32 v19, v19, v2
	v_mul_f32_e32 v2, v3, v2
	s_waitcnt vmcnt(60)
	v_lshlrev_b32_e32 v3, 16, v114
	v_lshlrev_b32_e32 v18, 16, v115
	v_lshlrev_b32_e32 v34, 16, v116
	v_lshlrev_b32_e32 v50, 16, v117
	v_mul_f32_e32 v77, 0xbfb8aa3b, v3
	v_mul_f32_e32 v80, 0xbfb8aa3b, v18
	v_mul_f32_e32 v81, 0xbfb8aa3b, v34
	v_mul_f32_e32 v82, 0xbfb8aa3b, v50
	v_exp_f32_e32 v77, v77
	v_exp_f32_e32 v80, v80
	v_exp_f32_e32 v81, v81
	v_exp_f32_e32 v82, v82
	v_add_f32_e32 v77, 1.0, v77
	v_add_f32_e32 v80, 1.0, v80
	v_add_f32_e32 v81, 1.0, v81
	v_add_f32_e32 v82, 1.0, v82
	v_rcp_f32_e32 v77, v77
	v_rcp_f32_e32 v80, v80
	v_rcp_f32_e32 v81, v81
	v_rcp_f32_e32 v82, v82
	v_mul_f32_e32 v3, v77, v3
	v_mul_f32_e32 v18, v80, v18
	v_mul_f32_e32 v34, v81, v34
	v_mul_f32_e32 v50, v82, v50
	v_mul_f32_e32 v3, v3, v51
	v_mul_f32_e32 v18, v35, v18
	v_mul_f32_e32 v19, v19, v34
	v_mul_f32_e32 v2, v2, v50
	v_cvt_pk_bf16_f32 v3, v3, s0
	v_cvt_pk_bf16_f32 v18, v18, s0
	v_cvt_pk_bf16_f32 v19, v19, s0
	v_cvt_pk_bf16_f32 v2, v2, s0
	global_store_short v[78:79], v3, off
	global_store_short v[78:79], v18, off offset:64
	global_store_short v[78:79], v19, off offset:128
	global_store_short v[78:79], v2, off offset:192
	v_or_b32_e32 v77, 2, v228
	v_lshlrev_b32_e32 v146, 10, v77
	v_lshl_add_u64 v[2:3], v[68:69], 0, v[146:147]
	v_mov_b32_e32 v18, v36
	v_mov_b32_e32 v19, v4
	v_mov_b32_e32 v50, v37
	v_mov_b32_e32 v51, v5
	v_mov_b32_e32 v2, v52
	v_mov_b32_e32 v3, v20
	v_mov_b32_e32 v34, v53
	v_mov_b32_e32 v35, v21
	v_pk_mul_f32 v[18:19], v[18:19], v[18:19]
	v_pk_mul_f32 v[50:51], v[50:51], v[50:51]
	v_pk_fma_f32 v[2:3], v[2:3], v[2:3], v[18:19]
	v_pk_fma_f32 v[18:19], v[34:35], v[34:35], v[50:51]
	v_mov_b32_e32 v35, v2
	v_mov_b32_e32 v34, v18
	v_mov_b32_e32 v2, v19
	v_pk_add_f32 v[2:3], v[34:35], v[2:3]
	s_nop 1
	v_mov_b32_dpp v19, v3 quad_perm:[1,0,3,2] row_mask:0xf bank_mask:0xf
	s_nop 1
	v_mov_b32_dpp v18, v2 quad_perm:[1,0,3,2] row_mask:0xf bank_mask:0xf
	v_lshlrev_b32_e32 v146, 11, v77
	s_waitcnt lgkmcnt(0)
	v_pk_add_f32 v[2:3], v[2:3], v[18:19]
	s_nop 1
	v_mov_b32_dpp v19, v3 quad_perm:[2,3,0,1] row_mask:0xf bank_mask:0xf
	s_nop 1
	v_mov_b32_dpp v18, v2 quad_perm:[2,3,0,1] row_mask:0xf bank_mask:0xf
	s_waitcnt lgkmcnt(0)
	v_pk_add_f32 v[2:3], v[2:3], v[18:19]
	s_nop 1
	v_mov_b32_dpp v19, v3 row_half_mirror row_mask:0xf bank_mask:0xf
	s_nop 1
	v_mov_b32_dpp v18, v2 row_half_mirror row_mask:0xf bank_mask:0xf
	s_waitcnt lgkmcnt(0)
; __device__ __forceinline__ float bf1(bf16_t h) { return __uint_as_float(((unsigned)h) << 16); }
; __device__ __forceinline__ bf16_t f2bf(float f) { return (bf16_t)(pk2(f, 0.f) & 0xffffu); }
; __device__ __forceinline__ float silu_t(float x) { return x * fast_sigmoid(x); }
; __device__ __forceinline__ int crow(int r, int hi) { return (r & 3) + 8 * (r >> 2) + 4 * hi; }
; __device__ __forceinline__ void ret_out_unit(bf16_t* Qb  , const bf16_t* __restrict__ Kh, const bf16_t* __restrict__ Vh, const bf16_t* __restrict__ Sf, const bf16_t* __restrict__ Sb,
;                                              const bf16_t* Gb, float lf2, float lb2, char* lds) {
;     ...
;   for (int r = 0; r < 16; ++r) {
;     float ss = (o[0][r] * o[0][r] + o[1][r] * o[1][r]) + (o[2][r] * o[2][r] + o[3][r] * o[3][r]);
; #pragma unroll
;     for (int off = 1; off < 32; off <<= 1) ss += __shfl_xor(ss, off);
;     const float rs = rsqrtf(ss * (1.f / 128.f) + EPS_N); const int orow = crow(r, hi);
; #pragma unroll
;     for (int d0 = 0; d0 < 4; ++d0) { const float g = bf1(Gw[(long)orow * 512 + d0 * 32 + r32]); Ow[(long)orow * 1024 + d0 * 32 + r32] = f2bf(o[d0][r] * rs * silu_t(g)); }
	v_pk_add_f32 v[2:3], v[2:3], v[18:19]
	s_nop 1
	v_mov_b32_dpp v19, v3 row_mirror row_mask:0xf bank_mask:0xf
	s_nop 1
	v_mov_b32_dpp v18, v2 row_mirror row_mask:0xf bank_mask:0xf
	s_waitcnt lgkmcnt(0)
	v_pk_add_f32 v[2:3], v[2:3], v[18:19]
	ds_bpermute_b32 v19, v76, v3
	ds_bpermute_b32 v18, v76, v2
	s_waitcnt lgkmcnt(0)
	v_pk_add_f32 v[2:3], v[2:3], v[18:19]
	s_nop 0
	v_pk_fma_f32 v[2:3], v[2:3], s[48:49], v[70:71] op_sel_hi:[1,0,0]
	s_waitcnt vmcnt(60)
	v_lshlrev_b32_e32 v50, 16, v120
	v_mul_f32_e32 v18, 0x4b800000, v3
	v_cmp_gt_f32_e64 s[4:5], s69, v3
	v_lshlrev_b32_e32 v51, 16, v121
	v_cmp_gt_f32_e32 vcc, s69, v2
	v_cndmask_b32_e64 v3, v3, v18, s[4:5]
	v_rsq_f32_e32 v3, v3
	v_lshl_add_u64 v[18:19], v[66:67], 0, v[146:147]
	v_mul_f32_e32 v34, 0x45800000, v3
	v_cndmask_b32_e64 v3, v3, v34, s[4:5]
	v_mul_f32_e32 v34, v52, v3
	v_mul_f32_e32 v35, v36, v3
	v_mul_f32_e32 v20, v20, v3
	v_mul_f32_e32 v3, v4, v3
	v_lshlrev_b32_e32 v4, 16, v118
	v_lshlrev_b32_e32 v36, 16, v119
	v_mul_f32_e32 v52, 0xbfb8aa3b, v4
	v_mul_f32_e32 v77, 0xbfb8aa3b, v36
	v_mul_f32_e32 v78, 0xbfb8aa3b, v50
	v_mul_f32_e32 v79, 0xbfb8aa3b, v51
	v_exp_f32_e32 v52, v52
	v_exp_f32_e32 v77, v77
	v_exp_f32_e32 v78, v78
	v_exp_f32_e32 v79, v79
	v_add_f32_e32 v52, 1.0, v52
	v_add_f32_e32 v77, 1.0, v77
	v_add_f32_e32 v78, 1.0, v78
	v_add_f32_e32 v79, 1.0, v79
	v_rcp_f32_e32 v52, v52
	v_rcp_f32_e32 v77, v77
	v_rcp_f32_e32 v78, v78
	v_rcp_f32_e32 v79, v79
	v_mul_f32_e32 v4, v52, v4
	v_mul_f32_e32 v36, v77, v36
	v_mul_f32_e32 v50, v78, v50
	v_mul_f32_e32 v51, v79, v51
	v_mul_f32_e32 v4, v4, v34
	v_mul_f32_e32 v34, v35, v36
	v_mul_f32_e32 v20, v20, v50
	v_mul_f32_e32 v3, v3, v51
	v_cvt_pk_bf16_f32 v4, v4, s0
	v_cvt_pk_bf16_f32 v34, v34, s0
	v_cvt_pk_bf16_f32 v20, v20, s0
	v_cvt_pk_bf16_f32 v3, v3, s0
	global_store_short v[18:19], v4, off
	global_store_short v[18:19], v34, off offset:64
	global_store_short v[18:19], v20, off offset:128
	global_store_short v[18:19], v3, off offset:192
	v_or_b32_e32 v3, 3, v228
	v_lshlrev_b32_e32 v146, 10, v3
	v_lshl_add_u64 v[18:19], v[68:69], 0, v[146:147]
	s_nop 0
	v_mul_f32_e32 v19, 0x4b800000, v2
	v_cndmask_b32_e32 v2, v2, v19, vcc
	v_rsq_f32_e32 v19, v2
	v_lshlrev_b32_e32 v146, 11, v3
	v_lshl_add_u64 v[2:3], v[66:67], 0, v[146:147]
	v_mul_f32_e32 v35, 0x45800000, v19
	v_cndmask_b32_e32 v19, v19, v35, vcc
	v_mul_f32_e32 v35, v53, v19
	v_mul_f32_e32 v36, v37, v19
	v_mul_f32_e32 v21, v21, v19
	v_mul_f32_e32 v5, v5, v19
	s_waitcnt vmcnt(60)
	v_lshlrev_b32_e32 v4, 16, v122
	v_lshlrev_b32_e32 v19, 16, v123
	v_lshlrev_b32_e32 v20, 16, v124
	v_lshlrev_b32_e32 v18, 16, v125
	v_mul_f32_e32 v34, 0xbfb8aa3b, v4
	v_mul_f32_e32 v37, 0xbfb8aa3b, v19
	v_mul_f32_e32 v50, 0xbfb8aa3b, v20
	v_mul_f32_e32 v51, 0xbfb8aa3b, v18
	v_exp_f32_e32 v34, v34
	v_exp_f32_e32 v37, v37
	v_exp_f32_e32 v50, v50
	v_exp_f32_e32 v51, v51
	v_add_f32_e32 v34, 1.0, v34
	v_add_f32_e32 v37, 1.0, v37
	v_add_f32_e32 v50, 1.0, v50
	v_add_f32_e32 v51, 1.0, v51
	v_rcp_f32_e32 v34, v34
	v_rcp_f32_e32 v37, v37
	v_rcp_f32_e32 v50, v50
	v_rcp_f32_e32 v51, v51
	v_mul_f32_e32 v4, v34, v4
	v_mul_f32_e32 v19, v37, v19
	v_mul_f32_e32 v20, v50, v20
	v_mul_f32_e32 v18, v51, v18
	v_mul_f32_e32 v4, v4, v35
	v_mul_f32_e32 v19, v36, v19
	v_mul_f32_e32 v20, v21, v20
	v_mul_f32_e32 v5, v5, v18
	v_cvt_pk_bf16_f32 v4, v4, s0
	v_cvt_pk_bf16_f32 v18, v19, s0
	v_cvt_pk_bf16_f32 v19, v20, s0
	v_cvt_pk_bf16_f32 v5, v5, s0
	global_store_short v[2:3], v4, off
	global_store_short v[2:3], v18, off offset:64
	global_store_short v[2:3], v19, off offset:128
	global_store_short v[2:3], v5, off offset:192
	v_or_b32_e32 v34, 8, v228
	v_lshlrev_b32_e32 v146, 10, v34
	v_lshl_add_u64 v[2:3], v[68:69], 0, v[146:147]
	v_mov_b32_e32 v4, v38
	v_mov_b32_e32 v5, v6
	v_mov_b32_e32 v20, v39
	v_mov_b32_e32 v21, v7
	v_mov_b32_e32 v2, v54
	v_mov_b32_e32 v3, v22
	v_mov_b32_e32 v18, v55
	v_mov_b32_e32 v19, v23
	v_pk_mul_f32 v[4:5], v[4:5], v[4:5]
	v_pk_mul_f32 v[20:21], v[20:21], v[20:21]
	v_pk_fma_f32 v[2:3], v[2:3], v[2:3], v[4:5]
	v_pk_fma_f32 v[4:5], v[18:19], v[18:19], v[20:21]
	v_mov_b32_e32 v19, v2
	v_mov_b32_e32 v18, v4
	v_mov_b32_e32 v2, v5
	v_pk_add_f32 v[2:3], v[18:19], v[2:3]
	s_nop 1
	v_mov_b32_dpp v5, v3 quad_perm:[1,0,3,2] row_mask:0xf bank_mask:0xf
	s_nop 1
	v_mov_b32_dpp v4, v2 quad_perm:[1,0,3,2] row_mask:0xf bank_mask:0xf
	v_lshlrev_b32_e32 v146, 11, v34
	s_waitcnt lgkmcnt(0)
	v_pk_add_f32 v[2:3], v[2:3], v[4:5]
	s_nop 1
	v_mov_b32_dpp v5, v3 quad_perm:[2,3,0,1] row_mask:0xf bank_mask:0xf
	s_nop 1
	v_mov_b32_dpp v4, v2 quad_perm:[2,3,0,1] row_mask:0xf bank_mask:0xf
	s_waitcnt lgkmcnt(0)
	v_pk_add_f32 v[2:3], v[2:3], v[4:5]
	s_nop 1
	v_mov_b32_dpp v5, v3 row_half_mirror row_mask:0xf bank_mask:0xf
	s_nop 1
	v_mov_b32_dpp v4, v2 row_half_mirror row_mask:0xf bank_mask:0xf
	s_waitcnt lgkmcnt(0)
	v_pk_add_f32 v[2:3], v[2:3], v[4:5]
	s_nop 1
	v_mov_b32_dpp v5, v3 row_mirror row_mask:0xf bank_mask:0xf
	s_nop 1
	v_mov_b32_dpp v4, v2 row_mirror row_mask:0xf bank_mask:0xf
	s_waitcnt lgkmcnt(0)
	v_pk_add_f32 v[2:3], v[2:3], v[4:5]
	ds_bpermute_b32 v5, v76, v3
	ds_bpermute_b32 v4, v76, v2
	s_waitcnt lgkmcnt(0)
	v_pk_add_f32 v[2:3], v[2:3], v[4:5]
	s_nop 0
	v_pk_fma_f32 v[2:3], v[2:3], s[48:49], v[70:71] op_sel_hi:[1,0,0]
	s_waitcnt vmcnt(60)
; __device__ __forceinline__ float bf1(bf16_t h) { return __uint_as_float(((unsigned)h) << 16); }
; __device__ __forceinline__ bf16_t f2bf(float f) { return (bf16_t)(pk2(f, 0.f) & 0xffffu); }
; __device__ __forceinline__ float silu_t(float x) { return x * fast_sigmoid(x); }
; __device__ __forceinline__ int crow(int r, int hi) { return (r & 3) + 8 * (r >> 2) + 4 * hi; }
; __device__ __forceinline__ void ret_out_unit(bf16_t* Qb  , const bf16_t* __restrict__ Kh, const bf16_t* __restrict__ Vh, const bf16_t* __restrict__ Sf, const bf16_t* __restrict__ Sb,
;                                              const bf16_t* Gb, float lf2, float lb2, char* lds) {
;     ...
;   for (int r = 0; r < 16; ++r) {
;     float ss = (o[0][r] * o[0][r] + o[1][r] * o[1][r]) + (o[2][r] * o[2][r] + o[3][r] * o[3][r]);
; #pragma unroll
;     for (int off = 1; off < 32; off <<= 1) ss += __shfl_xor(ss, off);
;     const float rs = rsqrtf(ss * (1.f / 128.f) + EPS_N); const int orow = crow(r, hi);
; #pragma unroll
;     for (int d0 = 0; d0 < 4; ++d0) { const float g = bf1(Gw[(long)orow * 512 + d0 * 32 + r32]); Ow[(long)orow * 1024 + d0 * 32 + r32] = f2bf(o[d0][r] * rs * silu_t(g)); }
	v_lshlrev_b32_e32 v21, 16, v127
	v_mul_f32_e32 v4, 0x4b800000, v3
	v_cmp_gt_f32_e64 s[4:5], s69, v3
	v_lshlrev_b32_e32 v34, 16, v129
	v_mul_f32_e32 v36, 0xbfb8aa3b, v21
	v_cndmask_b32_e64 v3, v3, v4, s[4:5]
	v_rsq_f32_e32 v3, v3
	v_exp_f32_e32 v36, v36
	v_lshl_add_u64 v[4:5], v[66:67], 0, v[146:147]
	v_cmp_gt_f32_e32 vcc, s69, v2
	v_mul_f32_e32 v18, 0x45800000, v3
	v_cndmask_b32_e64 v3, v3, v18, s[4:5]
	v_mul_f32_e32 v18, v54, v3
	v_mul_f32_e32 v19, v38, v3
	v_mul_f32_e32 v20, v22, v3
	v_mul_f32_e32 v3, v6, v3
	v_lshlrev_b32_e32 v6, 16, v126
	v_lshlrev_b32_e32 v22, 16, v128
	v_mul_f32_e32 v35, 0xbfb8aa3b, v6
	v_mul_f32_e32 v37, 0xbfb8aa3b, v22
	v_mul_f32_e32 v38, 0xbfb8aa3b, v34
	v_exp_f32_e32 v35, v35
	v_exp_f32_e32 v37, v37
	v_exp_f32_e32 v38, v38
	v_add_f32_e32 v36, 1.0, v36
	v_add_f32_e32 v35, 1.0, v35
	v_add_f32_e32 v37, 1.0, v37
	v_add_f32_e32 v38, 1.0, v38
	v_rcp_f32_e32 v35, v35
	v_rcp_f32_e32 v36, v36
	v_rcp_f32_e32 v37, v37
	v_rcp_f32_e32 v38, v38
	v_mul_f32_e32 v6, v35, v6
	v_mul_f32_e32 v21, v36, v21
	v_mul_f32_e32 v22, v37, v22
	v_mul_f32_e32 v34, v38, v34
	v_mul_f32_e32 v6, v6, v18
	v_mul_f32_e32 v18, v19, v21
	v_mul_f32_e32 v19, v20, v22
	v_mul_f32_e32 v3, v3, v34
	v_cvt_pk_bf16_f32 v6, v6, s0
	v_cvt_pk_bf16_f32 v18, v18, s0
	v_cvt_pk_bf16_f32 v19, v19, s0
	v_cvt_pk_bf16_f32 v3, v3, s0
	global_store_short v[4:5], v6, off
	global_store_short v[4:5], v18, off offset:64
	global_store_short v[4:5], v19, off offset:128
	global_store_short v[4:5], v3, off offset:192
	v_or_b32_e32 v3, 9, v228
	v_lshlrev_b32_e32 v146, 10, v3
	v_lshl_add_u64 v[4:5], v[68:69], 0, v[146:147]
	s_nop 0
	v_mul_f32_e32 v5, 0x4b800000, v2
	v_cndmask_b32_e32 v2, v2, v5, vcc
	v_rsq_f32_e32 v5, v2
	v_lshlrev_b32_e32 v146, 11, v3
	v_lshl_add_u64 v[2:3], v[66:67], 0, v[146:147]
	v_mul_f32_e32 v20, 0x45800000, v5
	v_cndmask_b32_e32 v5, v5, v20, vcc
	v_mul_f32_e32 v20, v55, v5
	v_mul_f32_e32 v21, v39, v5
	v_mul_f32_e32 v22, v23, v5
	v_mul_f32_e32 v5, v7, v5
	s_waitcnt vmcnt(60)
	v_lshlrev_b32_e32 v6, 16, v130
	v_lshlrev_b32_e32 v7, 16, v131
	v_lshlrev_b32_e32 v18, 16, v132
	v_lshlrev_b32_e32 v4, 16, v133
	v_mul_f32_e32 v19, 0xbfb8aa3b, v6
	v_mul_f32_e32 v23, 0xbfb8aa3b, v7
	v_mul_f32_e32 v34, 0xbfb8aa3b, v18
	v_mul_f32_e32 v35, 0xbfb8aa3b, v4
	v_exp_f32_e32 v19, v19
	v_exp_f32_e32 v23, v23
	v_exp_f32_e32 v34, v34
	v_exp_f32_e32 v35, v35
	v_add_f32_e32 v19, 1.0, v19
	v_add_f32_e32 v23, 1.0, v23
	v_add_f32_e32 v34, 1.0, v34
	v_add_f32_e32 v35, 1.0, v35
	v_rcp_f32_e32 v19, v19
	v_rcp_f32_e32 v23, v23
	v_rcp_f32_e32 v34, v34
	v_rcp_f32_e32 v35, v35
	v_mul_f32_e32 v6, v19, v6
	v_mul_f32_e32 v7, v23, v7
	v_mul_f32_e32 v18, v34, v18
	v_mul_f32_e32 v4, v35, v4
	v_mul_f32_e32 v6, v6, v20
	v_mul_f32_e32 v7, v21, v7
	v_mul_f32_e32 v18, v22, v18
	v_mul_f32_e32 v4, v5, v4
	v_cvt_pk_bf16_f32 v5, v6, s0
	v_cvt_pk_bf16_f32 v6, v7, s0
	v_cvt_pk_bf16_f32 v7, v18, s0
	v_cvt_pk_bf16_f32 v4, v4, s0
	global_store_short v[2:3], v5, off
	global_store_short v[2:3], v6, off offset:64
	global_store_short v[2:3], v7, off offset:128
	global_store_short v[2:3], v4, off offset:192
	v_or_b32_e32 v20, 10, v228
	v_lshlrev_b32_e32 v146, 10, v20
	v_lshl_add_u64 v[2:3], v[68:69], 0, v[146:147]
	v_mov_b32_e32 v4, v40
	v_mov_b32_e32 v5, v8
	v_mov_b32_e32 v18, v41
	v_mov_b32_e32 v19, v9
	v_mov_b32_e32 v2, v56
	v_mov_b32_e32 v3, v24
	v_mov_b32_e32 v6, v57
	v_mov_b32_e32 v7, v25
	v_pk_mul_f32 v[4:5], v[4:5], v[4:5]
	v_pk_mul_f32 v[18:19], v[18:19], v[18:19]
	v_pk_fma_f32 v[2:3], v[2:3], v[2:3], v[4:5]
	v_pk_fma_f32 v[4:5], v[6:7], v[6:7], v[18:19]
	v_mov_b32_e32 v7, v2
	v_mov_b32_e32 v6, v4
	v_mov_b32_e32 v2, v5
	v_pk_add_f32 v[2:3], v[6:7], v[2:3]
	s_nop 1
	v_mov_b32_dpp v5, v3 quad_perm:[1,0,3,2] row_mask:0xf bank_mask:0xf
	s_nop 1
	v_mov_b32_dpp v4, v2 quad_perm:[1,0,3,2] row_mask:0xf bank_mask:0xf
	v_lshlrev_b32_e32 v146, 11, v20
	s_waitcnt lgkmcnt(0)
	v_pk_add_f32 v[2:3], v[2:3], v[4:5]
	s_nop 1
	v_mov_b32_dpp v5, v3 quad_perm:[2,3,0,1] row_mask:0xf bank_mask:0xf
	s_nop 1
	v_mov_b32_dpp v4, v2 quad_perm:[2,3,0,1] row_mask:0xf bank_mask:0xf
	s_waitcnt lgkmcnt(0)
	v_pk_add_f32 v[2:3], v[2:3], v[4:5]
	s_nop 1
	v_mov_b32_dpp v5, v3 row_half_mirror row_mask:0xf bank_mask:0xf
	s_nop 1
	v_mov_b32_dpp v4, v2 row_half_mirror row_mask:0xf bank_mask:0xf
	s_waitcnt lgkmcnt(0)
	v_pk_add_f32 v[2:3], v[2:3], v[4:5]
	s_nop 1
	v_mov_b32_dpp v5, v3 row_mirror row_mask:0xf bank_mask:0xf
	s_nop 1
	v_mov_b32_dpp v4, v2 row_mirror row_mask:0xf bank_mask:0xf
	s_waitcnt lgkmcnt(0)
	v_pk_add_f32 v[2:3], v[2:3], v[4:5]
	ds_bpermute_b32 v5, v76, v3
	ds_bpermute_b32 v4, v76, v2
	s_waitcnt lgkmcnt(0)
	v_pk_add_f32 v[2:3], v[2:3], v[4:5]
	s_nop 0
	v_pk_fma_f32 v[2:3], v[2:3], s[48:49], v[70:71] op_sel_hi:[1,0,0]
	s_waitcnt vmcnt(60)
; __device__ __forceinline__ float bf1(bf16_t h) { return __uint_as_float(((unsigned)h) << 16); }
; __device__ __forceinline__ bf16_t f2bf(float f) { return (bf16_t)(pk2(f, 0.f) & 0xffffu); }
; __device__ __forceinline__ float silu_t(float x) { return x * fast_sigmoid(x); }
; __device__ __forceinline__ int crow(int r, int hi) { return (r & 3) + 8 * (r >> 2) + 4 * hi; }
; __device__ __forceinline__ void ret_out_unit(bf16_t* Qb  , const bf16_t* __restrict__ Kh, const bf16_t* __restrict__ Vh, const bf16_t* __restrict__ Sf, const bf16_t* __restrict__ Sb,
;                                              const bf16_t* Gb, float lf2, float lb2, char* lds) {
;     ...
;   for (int r = 0; r < 16; ++r) {
;     float ss = (o[0][r] * o[0][r] + o[1][r] * o[1][r]) + (o[2][r] * o[2][r] + o[3][r] * o[3][r]);
; #pragma unroll
;     for (int off = 1; off < 32; off <<= 1) ss += __shfl_xor(ss, off);
;     const float rs = rsqrtf(ss * (1.f / 128.f) + EPS_N); const int orow = crow(r, hi);
; #pragma unroll
;     for (int d0 = 0; d0 < 4; ++d0) { const float g = bf1(Gw[(long)orow * 512 + d0 * 32 + r32]); Ow[(long)orow * 1024 + d0 * 32 + r32] = f2bf(o[d0][r] * rs * silu_t(g)); }
	v_lshlrev_b32_e32 v19, 16, v135
	v_mul_f32_e32 v4, 0x4b800000, v3
	v_cmp_gt_f32_e64 s[4:5], s69, v3
	v_lshlrev_b32_e32 v20, 16, v136
	v_mul_f32_e32 v23, 0xbfb8aa3b, v19
	v_cndmask_b32_e64 v3, v3, v4, s[4:5]
	v_rsq_f32_e32 v3, v3
	v_exp_f32_e32 v23, v23
	v_lshl_add_u64 v[4:5], v[66:67], 0, v[146:147]
	v_cmp_gt_f32_e32 vcc, s69, v2
	v_mul_f32_e32 v6, 0x45800000, v3
	v_cndmask_b32_e64 v3, v3, v6, s[4:5]
	v_mul_f32_e32 v6, v56, v3
	v_mul_f32_e32 v7, v40, v3
	v_mul_f32_e32 v18, v24, v3
	v_mul_f32_e32 v3, v8, v3
	v_lshlrev_b32_e32 v8, 16, v134
	v_lshlrev_b32_e32 v21, 16, v137
	v_mul_f32_e32 v22, 0xbfb8aa3b, v8
	v_mul_f32_e32 v24, 0xbfb8aa3b, v20
	v_mul_f32_e32 v34, 0xbfb8aa3b, v21
	v_exp_f32_e32 v22, v22
	v_exp_f32_e32 v24, v24
	v_exp_f32_e32 v34, v34
	v_add_f32_e32 v23, 1.0, v23
	v_add_f32_e32 v22, 1.0, v22
	v_add_f32_e32 v24, 1.0, v24
	v_add_f32_e32 v34, 1.0, v34
	v_rcp_f32_e32 v22, v22
	v_rcp_f32_e32 v23, v23
	v_rcp_f32_e32 v24, v24
	v_rcp_f32_e32 v34, v34
	v_mul_f32_e32 v8, v22, v8
	v_mul_f32_e32 v19, v23, v19
	v_mul_f32_e32 v20, v24, v20
	v_mul_f32_e32 v21, v34, v21
	v_mul_f32_e32 v6, v8, v6
	v_mul_f32_e32 v7, v7, v19
	v_mul_f32_e32 v8, v18, v20
	v_mul_f32_e32 v3, v3, v21
	v_cvt_pk_bf16_f32 v6, v6, s0
	v_cvt_pk_bf16_f32 v7, v7, s0
	v_cvt_pk_bf16_f32 v8, v8, s0
	v_cvt_pk_bf16_f32 v3, v3, s0
	global_store_short v[4:5], v6, off
	global_store_short v[4:5], v7, off offset:64
	global_store_short v[4:5], v8, off offset:128
	global_store_short v[4:5], v3, off offset:192
	v_or_b32_e32 v3, 11, v228
	v_lshlrev_b32_e32 v146, 10, v3
	v_lshl_add_u64 v[4:5], v[68:69], 0, v[146:147]
	s_nop 0
	v_mul_f32_e32 v5, 0x4b800000, v2
	v_cndmask_b32_e32 v2, v2, v5, vcc
	v_rsq_f32_e32 v5, v2
	v_lshlrev_b32_e32 v146, 11, v3
	v_lshl_add_u64 v[2:3], v[66:67], 0, v[146:147]
	v_mul_f32_e32 v18, 0x45800000, v5
	v_cndmask_b32_e32 v5, v5, v18, vcc
	v_mul_f32_e32 v18, v57, v5
	v_mul_f32_e32 v19, v41, v5
	v_mul_f32_e32 v20, v25, v5
	v_mul_f32_e32 v5, v9, v5
	s_waitcnt vmcnt(60)
	v_lshlrev_b32_e32 v6, 16, v138
	v_lshlrev_b32_e32 v7, 16, v139
	v_lshlrev_b32_e32 v8, 16, v140
	v_lshlrev_b32_e32 v4, 16, v141
	v_mul_f32_e32 v9, 0xbfb8aa3b, v6
	v_mul_f32_e32 v21, 0xbfb8aa3b, v7
	v_mul_f32_e32 v22, 0xbfb8aa3b, v8
	v_mul_f32_e32 v23, 0xbfb8aa3b, v4
	v_exp_f32_e32 v9, v9
	v_exp_f32_e32 v21, v21
	v_exp_f32_e32 v22, v22
	v_exp_f32_e32 v23, v23
	v_add_f32_e32 v9, 1.0, v9
	v_add_f32_e32 v21, 1.0, v21
	v_add_f32_e32 v22, 1.0, v22
	v_add_f32_e32 v23, 1.0, v23
	v_rcp_f32_e32 v9, v9
	v_rcp_f32_e32 v21, v21
	v_rcp_f32_e32 v22, v22
	v_rcp_f32_e32 v23, v23
	v_mul_f32_e32 v6, v9, v6
	v_mul_f32_e32 v7, v21, v7
	v_mul_f32_e32 v8, v22, v8
	v_mul_f32_e32 v4, v23, v4
	v_mul_f32_e32 v6, v6, v18
	v_mul_f32_e32 v7, v19, v7
	v_mul_f32_e32 v8, v20, v8
	v_mul_f32_e32 v4, v5, v4
	v_cvt_pk_bf16_f32 v5, v6, s0
	v_cvt_pk_bf16_f32 v6, v7, s0
	v_cvt_pk_bf16_f32 v7, v8, s0
	v_cvt_pk_bf16_f32 v4, v4, s0
	global_store_short v[2:3], v5, off
	global_store_short v[2:3], v6, off offset:64
	global_store_short v[2:3], v7, off offset:128
	global_store_short v[2:3], v4, off offset:192
	v_or_b32_e32 v18, 16, v228
	v_lshlrev_b32_e32 v146, 10, v18
	v_lshl_add_u64 v[2:3], v[68:69], 0, v[146:147]
	v_mov_b32_e32 v4, v42
	v_mov_b32_e32 v5, v10
	v_mov_b32_e32 v8, v43
	v_mov_b32_e32 v9, v11
	v_mov_b32_e32 v2, v58
	v_mov_b32_e32 v3, v26
	v_mov_b32_e32 v6, v59
	v_mov_b32_e32 v7, v27
	v_pk_mul_f32 v[4:5], v[4:5], v[4:5]
	v_pk_mul_f32 v[8:9], v[8:9], v[8:9]
	v_pk_fma_f32 v[2:3], v[2:3], v[2:3], v[4:5]
	v_pk_fma_f32 v[4:5], v[6:7], v[6:7], v[8:9]
	v_mov_b32_e32 v7, v2
	v_mov_b32_e32 v6, v4
	v_mov_b32_e32 v2, v5
	v_pk_add_f32 v[2:3], v[6:7], v[2:3]
	s_nop 1
	v_mov_b32_dpp v5, v3 quad_perm:[1,0,3,2] row_mask:0xf bank_mask:0xf
	s_nop 1
	v_mov_b32_dpp v4, v2 quad_perm:[1,0,3,2] row_mask:0xf bank_mask:0xf
	v_lshlrev_b32_e32 v146, 11, v18
	s_waitcnt lgkmcnt(0)
	v_pk_add_f32 v[2:3], v[2:3], v[4:5]
	s_nop 1
	v_mov_b32_dpp v5, v3 quad_perm:[2,3,0,1] row_mask:0xf bank_mask:0xf
	s_nop 1
	v_mov_b32_dpp v4, v2 quad_perm:[2,3,0,1] row_mask:0xf bank_mask:0xf
	s_waitcnt lgkmcnt(0)
	v_pk_add_f32 v[2:3], v[2:3], v[4:5]
	s_nop 1
	v_mov_b32_dpp v5, v3 row_half_mirror row_mask:0xf bank_mask:0xf
	s_nop 1
	v_mov_b32_dpp v4, v2 row_half_mirror row_mask:0xf bank_mask:0xf
	s_waitcnt lgkmcnt(0)
	v_pk_add_f32 v[2:3], v[2:3], v[4:5]
	s_nop 1
	v_mov_b32_dpp v5, v3 row_mirror row_mask:0xf bank_mask:0xf
	s_nop 1
	v_mov_b32_dpp v4, v2 row_mirror row_mask:0xf bank_mask:0xf
	s_waitcnt lgkmcnt(0)
	v_pk_add_f32 v[2:3], v[2:3], v[4:5]
	ds_bpermute_b32 v5, v76, v3
	ds_bpermute_b32 v4, v76, v2
	s_waitcnt lgkmcnt(0)
	v_pk_add_f32 v[2:3], v[2:3], v[4:5]
	s_nop 0
	v_pk_fma_f32 v[2:3], v[2:3], s[48:49], v[70:71] op_sel_hi:[1,0,0]
	s_waitcnt vmcnt(60)
; __device__ __forceinline__ float bf1(bf16_t h) { return __uint_as_float(((unsigned)h) << 16); }
; __device__ __forceinline__ bf16_t f2bf(float f) { return (bf16_t)(pk2(f, 0.f) & 0xffffu); }
; __device__ __forceinline__ float silu_t(float x) { return x * fast_sigmoid(x); }
; __device__ __forceinline__ int crow(int r, int hi) { return (r & 3) + 8 * (r >> 2) + 4 * hi; }
; __device__ __forceinline__ void ret_out_unit(bf16_t* Qb  , const bf16_t* __restrict__ Kh, const bf16_t* __restrict__ Vh, const bf16_t* __restrict__ Sf, const bf16_t* __restrict__ Sb,
;                                              const bf16_t* Gb, float lf2, float lb2, char* lds) {
;     ...
;   for (int r = 0; r < 16; ++r) {
;     float ss = (o[0][r] * o[0][r] + o[1][r] * o[1][r]) + (o[2][r] * o[2][r] + o[3][r] * o[3][r]);
; #pragma unroll
;     for (int off = 1; off < 32; off <<= 1) ss += __shfl_xor(ss, off);
;     const float rs = rsqrtf(ss * (1.f / 128.f) + EPS_N); const int orow = crow(r, hi);
; #pragma unroll
;     for (int d0 = 0; d0 < 4; ++d0) { const float g = bf1(Gw[(long)orow * 512 + d0 * 32 + r32]); Ow[(long)orow * 1024 + d0 * 32 + r32] = f2bf(o[d0][r] * rs * silu_t(g)); }
	v_lshlrev_b32_e32 v9, 16, v142
	v_mul_f32_e32 v4, 0x4b800000, v3
	v_cmp_gt_f32_e64 s[4:5], s69, v3
	v_lshlrev_b32_e32 v18, 16, v144
	v_lshlrev_b32_e32 v19, 16, v145
	v_cndmask_b32_e64 v3, v3, v4, s[4:5]
	v_rsq_f32_e32 v3, v3
	v_mul_f32_e32 v22, 0xbfb8aa3b, v18
	v_mul_f32_e32 v23, 0xbfb8aa3b, v19
	v_exp_f32_e32 v22, v22
	v_mul_f32_e32 v6, 0x45800000, v3
	v_cndmask_b32_e64 v3, v3, v6, s[4:5]
	v_mul_f32_e32 v6, v58, v3
	v_mul_f32_e32 v7, v42, v3
	v_mul_f32_e32 v8, v26, v3
	v_mul_f32_e32 v3, v10, v3
	v_lshlrev_b32_e32 v10, 16, v143
	v_mul_f32_e32 v20, 0xbfb8aa3b, v9
	v_mul_f32_e32 v21, 0xbfb8aa3b, v10
	v_exp_f32_e32 v20, v20
	v_exp_f32_e32 v21, v21
	v_exp_f32_e32 v23, v23
	v_add_f32_e32 v22, 1.0, v22
	v_add_f32_e32 v20, 1.0, v20
	v_add_f32_e32 v21, 1.0, v21
	v_add_f32_e32 v23, 1.0, v23
	v_rcp_f32_e32 v20, v20
	v_rcp_f32_e32 v21, v21
	v_rcp_f32_e32 v22, v22
	v_rcp_f32_e32 v23, v23
	v_mul_f32_e32 v9, v20, v9
	v_mul_f32_e32 v10, v21, v10
	v_mul_f32_e32 v18, v22, v18
	v_mul_f32_e32 v19, v23, v19
	v_mul_f32_e32 v6, v9, v6
	v_lshl_add_u64 v[4:5], v[66:67], 0, v[146:147]
	v_mul_f32_e32 v7, v7, v10
	v_mul_f32_e32 v8, v8, v18
	v_mul_f32_e32 v3, v3, v19
	v_cvt_pk_bf16_f32 v6, v6, s0
	v_cmp_gt_f32_e32 vcc, s69, v2
	v_cvt_pk_bf16_f32 v7, v7, s0
	v_cvt_pk_bf16_f32 v8, v8, s0
	v_cvt_pk_bf16_f32 v3, v3, s0
	global_store_short v[4:5], v6, off
	global_store_short v[4:5], v7, off offset:64
	global_store_short v[4:5], v8, off offset:128
	global_store_short v[4:5], v3, off offset:192
	v_or_b32_e32 v3, 17, v228
	v_lshlrev_b32_e32 v146, 10, v3
	v_lshl_add_u64 v[4:5], v[68:69], 0, v[146:147]
	s_nop 0
	v_mul_f32_e32 v5, 0x4b800000, v2
	v_cndmask_b32_e32 v2, v2, v5, vcc
	v_rsq_f32_e32 v5, v2
	v_lshlrev_b32_e32 v146, 11, v3
	v_lshl_add_u64 v[2:3], v[66:67], 0, v[146:147]
	v_mul_f32_e32 v9, 0x45800000, v5
	v_cndmask_b32_e32 v5, v5, v9, vcc
	v_mul_f32_e32 v9, v59, v5
	v_mul_f32_e32 v10, v43, v5
	v_mul_f32_e32 v18, v27, v5
	v_mul_f32_e32 v5, v11, v5
	s_waitcnt vmcnt(60)
	v_lshlrev_b32_e32 v6, 16, v150
	v_lshlrev_b32_e32 v7, 16, v151
	v_lshlrev_b32_e32 v8, 16, v152
	v_lshlrev_b32_e32 v4, 16, v153
	v_mul_f32_e32 v11, 0xbfb8aa3b, v6
	v_mul_f32_e32 v19, 0xbfb8aa3b, v7
	v_mul_f32_e32 v20, 0xbfb8aa3b, v8
	v_mul_f32_e32 v21, 0xbfb8aa3b, v4
	v_exp_f32_e32 v11, v11
	v_exp_f32_e32 v19, v19
	v_exp_f32_e32 v20, v20
	v_exp_f32_e32 v21, v21
	v_add_f32_e32 v11, 1.0, v11
	v_add_f32_e32 v19, 1.0, v19
	v_add_f32_e32 v20, 1.0, v20
	v_add_f32_e32 v21, 1.0, v21
	v_rcp_f32_e32 v11, v11
	v_rcp_f32_e32 v19, v19
	v_rcp_f32_e32 v20, v20
	v_rcp_f32_e32 v21, v21
	v_mul_f32_e32 v6, v11, v6
	v_mul_f32_e32 v7, v19, v7
	v_mul_f32_e32 v8, v20, v8
	v_mul_f32_e32 v4, v21, v4
	v_mul_f32_e32 v6, v6, v9
	v_mul_f32_e32 v7, v10, v7
	v_mul_f32_e32 v8, v18, v8
	v_mul_f32_e32 v4, v5, v4
	v_cvt_pk_bf16_f32 v5, v6, s0
	v_cvt_pk_bf16_f32 v6, v7, s0
	v_cvt_pk_bf16_f32 v7, v8, s0
	v_cvt_pk_bf16_f32 v4, v4, s0
	global_store_short v[2:3], v5, off
	global_store_short v[2:3], v6, off offset:64
	global_store_short v[2:3], v7, off offset:128
	global_store_short v[2:3], v4, off offset:192
	v_or_b32_e32 v10, 18, v228
	v_lshlrev_b32_e32 v146, 10, v10
	v_lshl_add_u64 v[2:3], v[68:69], 0, v[146:147]
	v_mov_b32_e32 v4, v44
	v_mov_b32_e32 v5, v12
	v_mov_b32_e32 v8, v45
	v_mov_b32_e32 v9, v13
	v_mov_b32_e32 v2, v60
	v_mov_b32_e32 v3, v28
	v_mov_b32_e32 v6, v61
	v_mov_b32_e32 v7, v29
	v_pk_mul_f32 v[4:5], v[4:5], v[4:5]
	v_pk_mul_f32 v[8:9], v[8:9], v[8:9]
	v_pk_fma_f32 v[2:3], v[2:3], v[2:3], v[4:5]
	v_pk_fma_f32 v[4:5], v[6:7], v[6:7], v[8:9]
	v_mov_b32_e32 v7, v2
	v_mov_b32_e32 v6, v4
	v_mov_b32_e32 v2, v5
	v_pk_add_f32 v[2:3], v[6:7], v[2:3]
	s_nop 1
	v_mov_b32_dpp v5, v3 quad_perm:[1,0,3,2] row_mask:0xf bank_mask:0xf
	s_nop 1
	v_mov_b32_dpp v4, v2 quad_perm:[1,0,3,2] row_mask:0xf bank_mask:0xf
	v_lshlrev_b32_e32 v146, 11, v10
	s_waitcnt lgkmcnt(0)
	v_pk_add_f32 v[2:3], v[2:3], v[4:5]
	s_nop 1
	v_mov_b32_dpp v5, v3 quad_perm:[2,3,0,1] row_mask:0xf bank_mask:0xf
	s_nop 1
	v_mov_b32_dpp v4, v2 quad_perm:[2,3,0,1] row_mask:0xf bank_mask:0xf
	s_waitcnt lgkmcnt(0)
	v_pk_add_f32 v[2:3], v[2:3], v[4:5]
	s_nop 1
	v_mov_b32_dpp v5, v3 row_half_mirror row_mask:0xf bank_mask:0xf
	s_nop 1
	v_mov_b32_dpp v4, v2 row_half_mirror row_mask:0xf bank_mask:0xf
	s_waitcnt lgkmcnt(0)
	v_pk_add_f32 v[2:3], v[2:3], v[4:5]
	s_nop 1
	v_mov_b32_dpp v5, v3 row_mirror row_mask:0xf bank_mask:0xf
	s_nop 1
	v_mov_b32_dpp v4, v2 row_mirror row_mask:0xf bank_mask:0xf
	s_waitcnt lgkmcnt(0)
	v_pk_add_f32 v[2:3], v[2:3], v[4:5]
	ds_bpermute_b32 v5, v76, v3
	ds_bpermute_b32 v4, v76, v2
	s_waitcnt lgkmcnt(0)
	v_pk_add_f32 v[2:3], v[2:3], v[4:5]
	s_nop 0
	v_pk_fma_f32 v[2:3], v[2:3], s[48:49], v[70:71] op_sel_hi:[1,0,0]
	s_waitcnt vmcnt(60)
; __device__ __forceinline__ float bf1(bf16_t h) { return __uint_as_float(((unsigned)h) << 16); }
; __device__ __forceinline__ bf16_t f2bf(float f) { return (bf16_t)(pk2(f, 0.f) & 0xffffu); }
; __device__ __forceinline__ float silu_t(float x) { return x * fast_sigmoid(x); }
; #define SBAR() __builtin_amdgcn_sched_barrier(0)
; __device__ __forceinline__ int crow(int r, int hi) { return (r & 3) + 8 * (r >> 2) + 4 * hi; }
; __device__ __forceinline__ void ret_out_unit(bf16_t* Qb  , const bf16_t* __restrict__ Kh, const bf16_t* __restrict__ Vh, const bf16_t* __restrict__ Sf, const bf16_t* __restrict__ Sb,
;                                              const bf16_t* Gb, float lf2, float lb2, char* lds) {
;     ...
;   bf16_t* Ow = Qb + (long)(wid * QBLK) * 1024; const bf16_t* Gw = Gb + (long)(wid * QBLK) * 512;
; #pragma unroll
;   for (int r = 0; r < 16; ++r) {
;     float ss = (o[0][r] * o[0][r] + o[1][r] * o[1][r]) + (o[2][r] * o[2][r] + o[3][r] * o[3][r]);
; #pragma unroll
;     for (int off = 1; off < 32; off <<= 1) ss += __shfl_xor(ss, off);
;     const float rs = rsqrtf(ss * (1.f / 128.f) + EPS_N); const int orow = crow(r, hi);
; #pragma unroll
;     for (int d0 = 0; d0 < 4; ++d0) { const float g = bf1(Gw[(long)orow * 512 + d0 * 32 + r32]); Ow[(long)orow * 1024 + d0 * 32 + r32] = f2bf(o[d0][r] * rs * silu_t(g)); }
;     SBAR();
;   }
	v_lshlrev_b32_e32 v9, 16, v154
	v_mul_f32_e32 v4, 0x4b800000, v3
	v_cmp_gt_f32_e64 s[4:5], s69, v3
	v_lshlrev_b32_e32 v10, 16, v155
	v_lshlrev_b32_e32 v11, 16, v156
	v_cndmask_b32_e64 v3, v3, v4, s[4:5]
	v_rsq_f32_e32 v3, v3
	v_mul_f32_e32 v18, 0xbfb8aa3b, v9
	v_mul_f32_e32 v19, 0xbfb8aa3b, v10
	v_exp_f32_e32 v18, v18
	v_mul_f32_e32 v6, 0x45800000, v3
	v_cndmask_b32_e64 v3, v3, v6, s[4:5]
	v_mul_f32_e32 v6, v60, v3
	v_mul_f32_e32 v7, v44, v3
	v_mul_f32_e32 v8, v28, v3
	v_mul_f32_e32 v3, v12, v3
	v_lshlrev_b32_e32 v12, 16, v157
	v_mul_f32_e32 v20, 0xbfb8aa3b, v11
	v_mul_f32_e32 v21, 0xbfb8aa3b, v12
	v_exp_f32_e32 v19, v19
	v_exp_f32_e32 v20, v20
	v_exp_f32_e32 v21, v21
	v_add_f32_e32 v18, 1.0, v18
	v_add_f32_e32 v19, 1.0, v19
	v_add_f32_e32 v20, 1.0, v20
	v_add_f32_e32 v21, 1.0, v21
	v_rcp_f32_e32 v18, v18
	v_rcp_f32_e32 v19, v19
	v_rcp_f32_e32 v20, v20
	v_rcp_f32_e32 v21, v21
	v_mul_f32_e32 v9, v18, v9
	v_mul_f32_e32 v10, v19, v10
	v_mul_f32_e32 v11, v20, v11
	v_mul_f32_e32 v12, v21, v12
	v_mul_f32_e32 v6, v9, v6
	v_lshl_add_u64 v[4:5], v[66:67], 0, v[146:147]
	v_mul_f32_e32 v7, v7, v10
	v_mul_f32_e32 v8, v8, v11
	v_mul_f32_e32 v3, v3, v12
	v_cvt_pk_bf16_f32 v6, v6, s0
	v_cmp_gt_f32_e32 vcc, s69, v2
	v_cvt_pk_bf16_f32 v7, v7, s0
	v_cvt_pk_bf16_f32 v8, v8, s0
	v_cvt_pk_bf16_f32 v3, v3, s0
	global_store_short v[4:5], v6, off
	global_store_short v[4:5], v7, off offset:64
	global_store_short v[4:5], v8, off offset:128
	global_store_short v[4:5], v3, off offset:192
	v_or_b32_e32 v3, 19, v228
	v_lshlrev_b32_e32 v146, 10, v3
	v_lshl_add_u64 v[4:5], v[68:69], 0, v[146:147]
	s_nop 0
	v_mul_f32_e32 v5, 0x4b800000, v2
	v_cndmask_b32_e32 v2, v2, v5, vcc
	v_rsq_f32_e32 v5, v2
	v_lshlrev_b32_e32 v146, 11, v3
	v_lshl_add_u64 v[2:3], v[66:67], 0, v[146:147]
	v_mul_f32_e32 v9, 0x45800000, v5
	v_cndmask_b32_e32 v5, v5, v9, vcc
	v_mul_f32_e32 v9, v61, v5
	v_mul_f32_e32 v10, v45, v5
	v_mul_f32_e32 v11, v29, v5
	v_mul_f32_e32 v5, v13, v5
	s_waitcnt vmcnt(60)
	v_lshlrev_b32_e32 v6, 16, v158
	v_lshlrev_b32_e32 v7, 16, v159
	v_lshlrev_b32_e32 v8, 16, v160
	v_lshlrev_b32_e32 v4, 16, v161
	v_mul_f32_e32 v12, 0xbfb8aa3b, v6
	v_mul_f32_e32 v13, 0xbfb8aa3b, v7
	v_mul_f32_e32 v18, 0xbfb8aa3b, v8
	v_mul_f32_e32 v19, 0xbfb8aa3b, v4
	v_exp_f32_e32 v12, v12
	v_exp_f32_e32 v13, v13
	v_exp_f32_e32 v18, v18
	v_exp_f32_e32 v19, v19
	v_add_f32_e32 v12, 1.0, v12
	v_add_f32_e32 v13, 1.0, v13
	v_add_f32_e32 v18, 1.0, v18
	v_add_f32_e32 v19, 1.0, v19
	v_rcp_f32_e32 v12, v12
	v_rcp_f32_e32 v13, v13
	v_rcp_f32_e32 v18, v18
	v_rcp_f32_e32 v19, v19
	v_mul_f32_e32 v6, v12, v6
	v_mul_f32_e32 v7, v13, v7
	v_mul_f32_e32 v8, v18, v8
	v_mul_f32_e32 v4, v19, v4
	v_mul_f32_e32 v6, v6, v9
	v_mul_f32_e32 v7, v10, v7
	v_mul_f32_e32 v8, v11, v8
	v_mul_f32_e32 v4, v5, v4
	v_cvt_pk_bf16_f32 v5, v6, s0
	v_cvt_pk_bf16_f32 v6, v7, s0
	v_cvt_pk_bf16_f32 v7, v8, s0
	v_cvt_pk_bf16_f32 v4, v4, s0
	global_store_short v[2:3], v5, off
	global_store_short v[2:3], v6, off offset:64
	global_store_short v[2:3], v7, off offset:128
	global_store_short v[2:3], v4, off offset:192
	v_or_b32_e32 v10, 24, v228
	v_lshlrev_b32_e32 v146, 10, v10
	v_lshl_add_u64 v[2:3], v[68:69], 0, v[146:147]
	v_mov_b32_e32 v4, v46
	v_mov_b32_e32 v5, v14
	v_mov_b32_e32 v8, v47
	v_mov_b32_e32 v9, v15
	v_mov_b32_e32 v2, v62
	v_mov_b32_e32 v3, v30
	v_mov_b32_e32 v6, v63
	v_mov_b32_e32 v7, v31
	v_pk_mul_f32 v[4:5], v[4:5], v[4:5]
	v_pk_mul_f32 v[8:9], v[8:9], v[8:9]
	v_pk_fma_f32 v[2:3], v[2:3], v[2:3], v[4:5]
	v_pk_fma_f32 v[4:5], v[6:7], v[6:7], v[8:9]
	v_mov_b32_e32 v7, v2
	v_mov_b32_e32 v6, v4
	v_mov_b32_e32 v2, v5
	v_pk_add_f32 v[2:3], v[6:7], v[2:3]
	s_nop 1
	v_mov_b32_dpp v5, v3 quad_perm:[1,0,3,2] row_mask:0xf bank_mask:0xf
	s_nop 1
	v_mov_b32_dpp v4, v2 quad_perm:[1,0,3,2] row_mask:0xf bank_mask:0xf
	v_lshlrev_b32_e32 v146, 11, v10
	s_waitcnt lgkmcnt(0)
	v_pk_add_f32 v[2:3], v[2:3], v[4:5]
	s_nop 1
	v_mov_b32_dpp v5, v3 quad_perm:[2,3,0,1] row_mask:0xf bank_mask:0xf
	s_nop 1
	v_mov_b32_dpp v4, v2 quad_perm:[2,3,0,1] row_mask:0xf bank_mask:0xf
	s_waitcnt lgkmcnt(0)
	v_pk_add_f32 v[2:3], v[2:3], v[4:5]
	s_nop 1
	v_mov_b32_dpp v5, v3 row_half_mirror row_mask:0xf bank_mask:0xf
	s_nop 1
	v_mov_b32_dpp v4, v2 row_half_mirror row_mask:0xf bank_mask:0xf
	s_waitcnt lgkmcnt(0)
	v_pk_add_f32 v[2:3], v[2:3], v[4:5]
	s_nop 1
	v_mov_b32_dpp v5, v3 row_mirror row_mask:0xf bank_mask:0xf
	s_nop 1
	v_mov_b32_dpp v4, v2 row_mirror row_mask:0xf bank_mask:0xf
	s_waitcnt lgkmcnt(0)
	v_pk_add_f32 v[2:3], v[2:3], v[4:5]
	ds_bpermute_b32 v5, v76, v3
	ds_bpermute_b32 v4, v76, v2
	s_waitcnt lgkmcnt(0)
	v_pk_add_f32 v[2:3], v[2:3], v[4:5]
	s_nop 0
	v_pk_fma_f32 v[2:3], v[2:3], s[48:49], v[70:71] op_sel_hi:[1,0,0]
	s_waitcnt vmcnt(60)
; __device__ __forceinline__ float bf1(bf16_t h) { return __uint_as_float(((unsigned)h) << 16); }
; __device__ __forceinline__ bf16_t f2bf(float f) { return (bf16_t)(pk2(f, 0.f) & 0xffffu); }
; __device__ __forceinline__ float silu_t(float x) { return x * fast_sigmoid(x); }
; #define SBAR() __builtin_amdgcn_sched_barrier(0)
; __device__ __forceinline__ int crow(int r, int hi) { return (r & 3) + 8 * (r >> 2) + 4 * hi; }
; __device__ __forceinline__ void ret_out_unit(bf16_t* Qb  , const bf16_t* __restrict__ Kh, const bf16_t* __restrict__ Vh, const bf16_t* __restrict__ Sf, const bf16_t* __restrict__ Sb,
;                                              const bf16_t* Gb, float lf2, float lb2, char* lds) {
;     ...
;   bf16_t* Ow = Qb + (long)(wid * QBLK) * 1024; const bf16_t* Gw = Gb + (long)(wid * QBLK) * 512;
; #pragma unroll
;   for (int r = 0; r < 16; ++r) {
;     float ss = (o[0][r] * o[0][r] + o[1][r] * o[1][r]) + (o[2][r] * o[2][r] + o[3][r] * o[3][r]);
; #pragma unroll
;     for (int off = 1; off < 32; off <<= 1) ss += __shfl_xor(ss, off);
;     const float rs = rsqrtf(ss * (1.f / 128.f) + EPS_N); const int orow = crow(r, hi);
; #pragma unroll
;     for (int d0 = 0; d0 < 4; ++d0) { const float g = bf1(Gw[(long)orow * 512 + d0 * 32 + r32]); Ow[(long)orow * 1024 + d0 * 32 + r32] = f2bf(o[d0][r] * rs * silu_t(g)); }
;     SBAR();
;   }
	v_lshlrev_b32_e32 v9, 16, v162
	v_mul_f32_e32 v4, 0x4b800000, v3
	v_cmp_gt_f32_e64 s[4:5], s69, v3
	v_lshlrev_b32_e32 v10, 16, v163
	v_lshlrev_b32_e32 v11, 16, v164
	v_cndmask_b32_e64 v3, v3, v4, s[4:5]
	v_rsq_f32_e32 v3, v3
	v_lshlrev_b32_e32 v12, 16, v165
	v_mul_f32_e32 v13, 0xbfb8aa3b, v9
	v_mul_f32_e32 v18, 0xbfb8aa3b, v11
	v_mul_f32_e32 v6, 0x45800000, v3
	v_cndmask_b32_e64 v3, v3, v6, s[4:5]
	v_mul_f32_e32 v6, v62, v3
	v_mul_f32_e32 v7, v46, v3
	v_mul_f32_e32 v8, v30, v3
	v_mul_f32_e32 v3, v14, v3
	v_mul_f32_e32 v14, 0xbfb8aa3b, v10
	v_mul_f32_e32 v19, 0xbfb8aa3b, v12
	v_exp_f32_e32 v13, v13
	v_exp_f32_e32 v14, v14
	v_exp_f32_e32 v18, v18
	v_exp_f32_e32 v19, v19
	v_add_f32_e32 v13, 1.0, v13
	v_add_f32_e32 v14, 1.0, v14
	v_add_f32_e32 v18, 1.0, v18
	v_add_f32_e32 v19, 1.0, v19
	v_rcp_f32_e32 v13, v13
	v_rcp_f32_e32 v14, v14
	v_rcp_f32_e32 v18, v18
	v_rcp_f32_e32 v19, v19
	v_mul_f32_e32 v9, v13, v9
	v_mul_f32_e32 v10, v14, v10
	v_mul_f32_e32 v11, v18, v11
	v_mul_f32_e32 v12, v19, v12
	v_mul_f32_e32 v6, v9, v6
	v_lshl_add_u64 v[4:5], v[66:67], 0, v[146:147]
	v_mul_f32_e32 v7, v7, v10
	v_mul_f32_e32 v8, v8, v11
	v_mul_f32_e32 v3, v3, v12
	v_cvt_pk_bf16_f32 v6, v6, s0
	v_cmp_gt_f32_e32 vcc, s69, v2
	v_cvt_pk_bf16_f32 v7, v7, s0
	v_cvt_pk_bf16_f32 v8, v8, s0
	v_cvt_pk_bf16_f32 v3, v3, s0
	global_store_short v[4:5], v6, off
	global_store_short v[4:5], v7, off offset:64
	global_store_short v[4:5], v8, off offset:128
	global_store_short v[4:5], v3, off offset:192
	v_or_b32_e32 v3, 25, v228
	v_lshlrev_b32_e32 v146, 10, v3
	v_lshl_add_u64 v[4:5], v[68:69], 0, v[146:147]
	s_nop 0
	v_mul_f32_e32 v5, 0x4b800000, v2
	v_cndmask_b32_e32 v2, v2, v5, vcc
	v_rsq_f32_e32 v5, v2
	v_lshlrev_b32_e32 v146, 11, v3
	v_lshl_add_u64 v[2:3], v[66:67], 0, v[146:147]
	v_mul_f32_e32 v9, 0x45800000, v5
	v_cndmask_b32_e32 v5, v5, v9, vcc
	v_mul_f32_e32 v9, v63, v5
	v_mul_f32_e32 v10, v47, v5
	v_mul_f32_e32 v11, v31, v5
	v_mul_f32_e32 v5, v15, v5
	s_waitcnt vmcnt(60)
	v_lshlrev_b32_e32 v6, 16, v166
	v_lshlrev_b32_e32 v7, 16, v167
	v_lshlrev_b32_e32 v8, 16, v168
	v_lshlrev_b32_e32 v4, 16, v169
	v_mul_f32_e32 v12, 0xbfb8aa3b, v6
	v_mul_f32_e32 v13, 0xbfb8aa3b, v7
	v_mul_f32_e32 v14, 0xbfb8aa3b, v8
	v_mul_f32_e32 v15, 0xbfb8aa3b, v4
	v_exp_f32_e32 v12, v12
	v_exp_f32_e32 v13, v13
	v_exp_f32_e32 v14, v14
	v_exp_f32_e32 v15, v15
	v_add_f32_e32 v12, 1.0, v12
	v_add_f32_e32 v13, 1.0, v13
	v_add_f32_e32 v14, 1.0, v14
	v_add_f32_e32 v15, 1.0, v15
	v_rcp_f32_e32 v12, v12
	v_rcp_f32_e32 v13, v13
	v_rcp_f32_e32 v14, v14
	v_rcp_f32_e32 v15, v15
	v_mul_f32_e32 v6, v12, v6
	v_mul_f32_e32 v7, v13, v7
	v_mul_f32_e32 v8, v14, v8
	v_mul_f32_e32 v4, v15, v4
	v_mul_f32_e32 v6, v6, v9
	v_mul_f32_e32 v7, v10, v7
	v_mul_f32_e32 v8, v11, v8
	v_mul_f32_e32 v4, v5, v4
	v_cvt_pk_bf16_f32 v5, v6, s0
	v_cvt_pk_bf16_f32 v6, v7, s0
	v_cvt_pk_bf16_f32 v7, v8, s0
	v_cvt_pk_bf16_f32 v4, v4, s0
	global_store_short v[2:3], v5, off
	global_store_short v[2:3], v6, off offset:64
	global_store_short v[2:3], v7, off offset:128
	global_store_short v[2:3], v4, off offset:192
	v_or_b32_e32 v10, 26, v228
	v_lshlrev_b32_e32 v146, 10, v10
	v_lshl_add_u64 v[2:3], v[68:69], 0, v[146:147]
	v_mov_b32_e32 v4, v48
	v_mov_b32_e32 v5, v16
	v_mov_b32_e32 v8, v49
	v_mov_b32_e32 v9, v17
	v_mov_b32_e32 v2, v64
	v_mov_b32_e32 v3, v32
	v_mov_b32_e32 v6, v65
	v_mov_b32_e32 v7, v33
	v_pk_mul_f32 v[4:5], v[4:5], v[4:5]
	v_pk_mul_f32 v[8:9], v[8:9], v[8:9]
	v_pk_fma_f32 v[2:3], v[2:3], v[2:3], v[4:5]
	v_pk_fma_f32 v[4:5], v[6:7], v[6:7], v[8:9]
	v_mov_b32_e32 v7, v2
	v_mov_b32_e32 v6, v4
	v_mov_b32_e32 v2, v5
	v_pk_add_f32 v[2:3], v[6:7], v[2:3]
	s_nop 1
	v_mov_b32_dpp v5, v3 quad_perm:[1,0,3,2] row_mask:0xf bank_mask:0xf
	s_nop 1
	v_mov_b32_dpp v4, v2 quad_perm:[1,0,3,2] row_mask:0xf bank_mask:0xf
	v_lshlrev_b32_e32 v146, 11, v10
	s_waitcnt lgkmcnt(0)
; __device__ __forceinline__ float bf1(bf16_t h) { return __uint_as_float(((unsigned)h) << 16); }
; __device__ __forceinline__ bf16_t f2bf(float f) { return (bf16_t)(pk2(f, 0.f) & 0xffffu); }
; __device__ __forceinline__ float silu_t(float x) { return x * fast_sigmoid(x); }
; #define SBAR() __builtin_amdgcn_sched_barrier(0)
; __device__ __forceinline__ int crow(int r, int hi) { return (r & 3) + 8 * (r >> 2) + 4 * hi; }
; __device__ __forceinline__ void ret_out_unit(bf16_t* Qb  , const bf16_t* __restrict__ Kh, const bf16_t* __restrict__ Vh, const bf16_t* __restrict__ Sf, const bf16_t* __restrict__ Sb,
;                                              const bf16_t* Gb, float lf2, float lb2, char* lds) {
;     ...
;   bf16_t* Ow = Qb + (long)(wid * QBLK) * 1024; const bf16_t* Gw = Gb + (long)(wid * QBLK) * 512;
; #pragma unroll
;   for (int r = 0; r < 16; ++r) {
;     float ss = (o[0][r] * o[0][r] + o[1][r] * o[1][r]) + (o[2][r] * o[2][r] + o[3][r] * o[3][r]);
; #pragma unroll
;     for (int off = 1; off < 32; off <<= 1) ss += __shfl_xor(ss, off);
;     const float rs = rsqrtf(ss * (1.f / 128.f) + EPS_N); const int orow = crow(r, hi);
; #pragma unroll
;     for (int d0 = 0; d0 < 4; ++d0) { const float g = bf1(Gw[(long)orow * 512 + d0 * 32 + r32]); Ow[(long)orow * 1024 + d0 * 32 + r32] = f2bf(o[d0][r] * rs * silu_t(g)); }
;     SBAR();
;   }
;   __syncthreads();
	v_pk_add_f32 v[2:3], v[2:3], v[4:5]
	s_nop 1
	v_mov_b32_dpp v5, v3 quad_perm:[2,3,0,1] row_mask:0xf bank_mask:0xf
	s_nop 1
	v_mov_b32_dpp v4, v2 quad_perm:[2,3,0,1] row_mask:0xf bank_mask:0xf
	s_waitcnt lgkmcnt(0)
	v_pk_add_f32 v[2:3], v[2:3], v[4:5]
	s_nop 1
	v_mov_b32_dpp v5, v3 row_half_mirror row_mask:0xf bank_mask:0xf
	s_nop 1
	v_mov_b32_dpp v4, v2 row_half_mirror row_mask:0xf bank_mask:0xf
	s_waitcnt lgkmcnt(0)
	v_pk_add_f32 v[2:3], v[2:3], v[4:5]
	s_nop 1
	v_mov_b32_dpp v5, v3 row_mirror row_mask:0xf bank_mask:0xf
	s_nop 1
	v_mov_b32_dpp v4, v2 row_mirror row_mask:0xf bank_mask:0xf
	s_waitcnt lgkmcnt(0)
	v_pk_add_f32 v[2:3], v[2:3], v[4:5]
	ds_bpermute_b32 v5, v76, v3
	ds_bpermute_b32 v4, v76, v2
	s_waitcnt lgkmcnt(0)
	v_pk_add_f32 v[2:3], v[2:3], v[4:5]
	s_nop 0
	v_pk_fma_f32 v[2:3], v[2:3], s[48:49], v[70:71] op_sel_hi:[1,0,0]
	s_waitcnt vmcnt(60)
	v_lshlrev_b32_e32 v9, 16, v172
	v_mul_f32_e32 v4, 0x4b800000, v3
	v_cmp_gt_f32_e64 s[4:5], s69, v3
	v_lshlrev_b32_e32 v10, 16, v173
	v_lshlrev_b32_e32 v11, 16, v174
	v_cndmask_b32_e64 v3, v3, v4, s[4:5]
	v_rsq_f32_e32 v3, v3
	v_lshlrev_b32_e32 v12, 16, v175
	v_mul_f32_e32 v13, 0xbfb8aa3b, v9
	v_mul_f32_e32 v14, 0xbfb8aa3b, v10
	v_mul_f32_e32 v6, 0x45800000, v3
	v_cndmask_b32_e64 v3, v3, v6, s[4:5]
	v_mul_f32_e32 v6, v64, v3
	v_mul_f32_e32 v7, v48, v3
	v_mul_f32_e32 v8, v32, v3
	v_mul_f32_e32 v3, v16, v3
	v_mul_f32_e32 v15, 0xbfb8aa3b, v11
	v_mul_f32_e32 v16, 0xbfb8aa3b, v12
	v_exp_f32_e32 v13, v13
	v_exp_f32_e32 v14, v14
	v_exp_f32_e32 v15, v15
	v_exp_f32_e32 v16, v16
	v_add_f32_e32 v13, 1.0, v13
	v_add_f32_e32 v14, 1.0, v14
	v_add_f32_e32 v15, 1.0, v15
	v_add_f32_e32 v16, 1.0, v16
	v_rcp_f32_e32 v13, v13
	v_rcp_f32_e32 v14, v14
	v_rcp_f32_e32 v15, v15
	v_rcp_f32_e32 v16, v16
	v_mul_f32_e32 v9, v13, v9
	v_mul_f32_e32 v10, v14, v10
	v_mul_f32_e32 v11, v15, v11
	v_mul_f32_e32 v12, v16, v12
	v_mul_f32_e32 v6, v9, v6
	v_lshl_add_u64 v[4:5], v[66:67], 0, v[146:147]
	v_mul_f32_e32 v7, v7, v10
	v_mul_f32_e32 v8, v8, v11
	v_mul_f32_e32 v3, v3, v12
	v_cvt_pk_bf16_f32 v6, v6, s0
	v_cmp_gt_f32_e32 vcc, s69, v2
	v_cvt_pk_bf16_f32 v7, v7, s0
	v_cvt_pk_bf16_f32 v8, v8, s0
	v_cvt_pk_bf16_f32 v3, v3, s0
	global_store_short v[4:5], v6, off
	global_store_short v[4:5], v7, off offset:64
	global_store_short v[4:5], v8, off offset:128
	global_store_short v[4:5], v3, off offset:192
	v_or_b32_e32 v3, 27, v228
	v_lshlrev_b32_e32 v146, 10, v3
	v_lshl_add_u64 v[4:5], v[68:69], 0, v[146:147]
	s_nop 0
	v_mul_f32_e32 v5, 0x4b800000, v2
	v_cndmask_b32_e32 v2, v2, v5, vcc
	v_rsq_f32_e32 v5, v2
	v_lshlrev_b32_e32 v146, 11, v3
	v_lshl_add_u64 v[2:3], v[66:67], 0, v[146:147]
	v_mul_f32_e32 v9, 0x45800000, v5
	v_cndmask_b32_e32 v5, v5, v9, vcc
	v_mul_f32_e32 v9, v65, v5
	v_mul_f32_e32 v10, v49, v5
	v_mul_f32_e32 v11, v33, v5
	v_mul_f32_e32 v5, v17, v5
	s_waitcnt vmcnt(60)
	v_lshlrev_b32_e32 v6, 16, v176
	v_lshlrev_b32_e32 v7, 16, v177
	v_lshlrev_b32_e32 v8, 16, v178
	v_lshlrev_b32_e32 v4, 16, v179
	v_mul_f32_e32 v12, 0xbfb8aa3b, v6
	v_mul_f32_e32 v13, 0xbfb8aa3b, v7
	v_mul_f32_e32 v14, 0xbfb8aa3b, v8
	v_mul_f32_e32 v15, 0xbfb8aa3b, v4
	v_exp_f32_e32 v12, v12
	v_exp_f32_e32 v13, v13
	v_exp_f32_e32 v14, v14
	v_exp_f32_e32 v15, v15
	v_add_f32_e32 v12, 1.0, v12
	v_add_f32_e32 v13, 1.0, v13
	v_add_f32_e32 v14, 1.0, v14
	v_add_f32_e32 v15, 1.0, v15
	v_rcp_f32_e32 v12, v12
	v_rcp_f32_e32 v13, v13
	v_rcp_f32_e32 v14, v14
	v_rcp_f32_e32 v15, v15
	v_mul_f32_e32 v6, v12, v6
	v_mul_f32_e32 v7, v13, v7
	v_mul_f32_e32 v8, v14, v8
	v_mul_f32_e32 v4, v15, v4
	v_mul_f32_e32 v6, v6, v9
	v_mul_f32_e32 v7, v10, v7
	v_mul_f32_e32 v8, v11, v8
	v_mul_f32_e32 v4, v5, v4
	v_cvt_pk_bf16_f32 v5, v6, s0
	v_cvt_pk_bf16_f32 v6, v7, s0
	v_cvt_pk_bf16_f32 v7, v8, s0
	v_cvt_pk_bf16_f32 v4, v4, s0
	global_store_short v[2:3], v5, off
	global_store_short v[2:3], v6, off offset:64
	global_store_short v[2:3], v7, off offset:128
	global_store_short v[2:3], v4, off offset:192
	s_movk_i32 s6, 0x100
	s_andn2_b64 vcc, exec, s[54:55]
	s_mov_b64 s[4:5], 0
	s_barrier
	s_cbranch_vccz .LBB0_1971
